# X2 prompt: second pair's Q rows requested during the first pair's PV
# baseline (speedup 1.0000x reference)
; #define MFMA16(a, b, c) __builtin_amdgcn_mfma_f32_16x16x32_bf16((a), (b), (c), 0, 0, 0)
; __device__ __forceinline__ float bf_lo(unsigned w) { return __uint_as_float(w << 16); }
; __device__ __forceinline__ float bf_hi(unsigned w) { return __uint_as_float(w & 0xffff0000u); }
; __device__ __forceinline__ unsigned pk2(float lo, float hi) { return pg8::cvt_pk_bf16(lo, hi); }
; __device__ __forceinline__ void xattn_prompt_item(const bf16_t* xq, const bf16_t* xq1, const bf16_t* memkv, const bf16_t* memvt, bf16_t* xo, int l, int it, int lane) {
;     const int h = it & 3, qt = it >> 2, b = qt >> 8;
;     const int l15 = lane & 15, g = lane >> 4;
;     const size_t tok = (size_t)qt * 16 + l15;
;     bf16x8 qf[4];
; #pragma unroll
;     for (int ks = 0; ks < 4; ++ks) {
;         const u32x4 a = *(const u32x4*)(xq + tok * 512 + h * 128 + 32 * ks + 8 * g), c = *(const u32x4*)(xq1 + tok * 512 + h * 128 + 32 * ks + 8 * g);
;         u32x4 w; w.x = pk2(bf_lo(a.x) + bf_lo(c.x), bf_hi(a.x) + bf_hi(c.x)); w.y = pk2(bf_lo(a.y) + bf_lo(c.y), bf_hi(a.y) + bf_hi(c.y));
;         w.z = pk2(bf_lo(a.z) + bf_lo(c.z), bf_hi(a.z) + bf_hi(c.z)); w.w = pk2(bf_lo(a.w) + bf_lo(c.w), bf_hi(a.w) + bf_hi(c.w));
;         qf[ks] = as_bf16x8(w);
;     }
;     f32x4 sc[16];
;     float mx = -1e30f;
; #pragma unroll
;     for (int kt = 0; kt < 16; ++kt) {
;         const bf16_t* kp = memkv + ((size_t)b * 256 + 16 * kt + l15) * 4096 + l * 1024 + h * 128 + 8 * g;
;         f32x4 a = {0.f, 0.f, 0.f, 0.f};
; #pragma unroll
;         for (int ks = 0; ks < 4; ++ks) a = MFMA16(*(const bf16x8*)(kp + 32 * ks), qf[ks], a);
.Lxp_pair:
	s_and_b32 s7, s6, 3
	s_lshr_b32 s4, s6, 2
	s_lshr_b32 s5, s4, 5
	s_lshl_b32 s4, s4, 3
	s_ashr_i32 s16, s27, 6
	s_add_i32 s4, s4, s16
	s_lshl_b32 s80, s7, 8
	s_lshl_b32 s4, s4, 14
	s_add_i32 s4, s4, s80
	s_add_u32 s22, s10, s4
	s_addc_u32 s23, s11, 0
	s_add_u32 s24, s12, s4
	s_addc_u32 s25, s13, 0
	s_cmp_lg_u32 s28, 0
	s_cbranch_scc1 .Lxp_nostage
	global_load_dwordx4 v[26:29], v2, s[22:23] offset:0
	global_load_dwordx4 v[30:33], v2, s[22:23] offset:64
	global_load_dwordx4 v[34:37], v2, s[22:23] offset:128
	global_load_dwordx4 v[38:41], v2, s[22:23] offset:192
	global_load_dwordx4 v[42:45], v2, s[24:25] offset:0
	global_load_dwordx4 v[46:49], v2, s[24:25] offset:64
	global_load_dwordx4 v[50:53], v2, s[24:25] offset:128
	global_load_dwordx4 v[54:57], v2, s[24:25] offset:192
	v_readlane_b32 s18, v254, 42
	v_readlane_b32 s19, v254, 43
	v_readlane_b32 s20, v254, 38
	s_nop 0
	s_lshl_b32 s21, s20, 11
	s_add_i32 s21, s21, s80
	s_lshl_b32 s16, s5, 21
	s_add_i32 s21, s21, s16
	s_add_u32 s16, s18, 0x28c28000
	s_addc_u32 s17, s19, 0
	s_add_u32 s16, s16, s21
	s_addc_u32 s17, s17, 0
	s_lshl_b32 s20, s20, 1
	s_add_i32 s20, s20, s5
	s_lshl_b32 s20, s20, 18
	s_lshl_b32 s21, s7, 16
	s_add_i32 s21, s21, s20
	s_add_u32 s20, s18, 0x29028000
	s_addc_u32 s19, s19, 0
	s_add_u32 s20, s20, s21
	s_addc_u32 s21, s19, 0
	s_add_u32 s4, s14, s4
	s_addc_u32 s5, s15, 0
	global_load_dwordx4 v[146:149], v58, s[16:17]
	s_add_u32 s16, s16, 0x40000
	s_addc_u32 s17, s17, 0
	global_load_dwordx4 v[150:153], v58, s[16:17]
	s_add_u32 s16, s16, 0x40000
	s_addc_u32 s17, s17, 0
	global_load_dwordx4 v[154:157], v58, s[16:17]
	s_add_u32 s16, s16, 0x40000
	s_addc_u32 s17, s17, 0
	global_load_dwordx4 v[158:161], v58, s[16:17]
	s_add_u32 s16, s16, 0x40000
	s_addc_u32 s17, s17, 0
	global_load_dwordx4 v[162:165], v58, s[16:17]
	s_add_u32 s16, s16, 0x40000
	s_addc_u32 s17, s17, 0
	global_load_dwordx4 v[166:169], v58, s[16:17]
	s_add_u32 s16, s16, 0x40000
	s_addc_u32 s17, s17, 0
	global_load_dwordx4 v[170:173], v58, s[16:17]
	s_add_u32 s16, s16, 0x40000
	s_addc_u32 s17, s17, 0
	global_load_dwordx4 v[174:177], v58, s[16:17]
	global_load_dwordx4 v[178:181], v60, s[20:21]
	s_add_u32 s20, s20, 0x2000
	s_addc_u32 s21, s21, 0
	global_load_dwordx4 v[182:185], v60, s[20:21]
	s_add_u32 s20, s20, 0x2000
	s_addc_u32 s21, s21, 0
	global_load_dwordx4 v[186:189], v60, s[20:21]
	s_add_u32 s20, s20, 0x2000
	s_addc_u32 s21, s21, 0
	global_load_dwordx4 v[190:193], v60, s[20:21]
	s_add_u32 s20, s20, 0x2000
	s_addc_u32 s21, s21, 0
	global_load_dwordx4 v[194:197], v60, s[20:21]
	s_add_u32 s20, s20, 0x2000
	s_addc_u32 s21, s21, 0
	global_load_dwordx4 v[198:201], v60, s[20:21]
	s_add_u32 s20, s20, 0x2000
	s_addc_u32 s21, s21, 0
	global_load_dwordx4 v[202:205], v60, s[20:21]
	s_add_u32 s20, s20, 0x2000
	s_addc_u32 s21, s21, 0
	global_load_dwordx4 v[206:209], v60, s[20:21]
	s_waitcnt vmcnt(16)
	v_lshlrev_b32_e32 v8, 16, v26
	v_and_b32_e32 v9, 0xffff0000, v26
	v_lshlrev_b32_e32 v136, 16, v42
	v_and_b32_e32 v137, 0xffff0000, v42
	v_pk_add_f32 v[8:9], v[8:9], v[136:137]
	v_cvt_pk_bf16_f32 v10, v8, v9
	v_lshlrev_b32_e32 v8, 16, v27
	v_and_b32_e32 v9, 0xffff0000, v27
	v_lshlrev_b32_e32 v136, 16, v43
	v_and_b32_e32 v137, 0xffff0000, v43
	v_pk_add_f32 v[8:9], v[8:9], v[136:137]
	v_cvt_pk_bf16_f32 v11, v8, v9
	v_lshlrev_b32_e32 v8, 16, v28
	v_and_b32_e32 v9, 0xffff0000, v28
	v_lshlrev_b32_e32 v136, 16, v44
	v_and_b32_e32 v137, 0xffff0000, v44
	v_pk_add_f32 v[8:9], v[8:9], v[136:137]
	v_cvt_pk_bf16_f32 v12, v8, v9
	v_lshlrev_b32_e32 v8, 16, v29
	v_and_b32_e32 v9, 0xffff0000, v29
	v_lshlrev_b32_e32 v136, 16, v45
	v_and_b32_e32 v137, 0xffff0000, v45
	v_pk_add_f32 v[8:9], v[8:9], v[136:137]
	v_cvt_pk_bf16_f32 v13, v8, v9
	v_lshlrev_b32_e32 v8, 16, v30
	v_and_b32_e32 v9, 0xffff0000, v30
	v_lshlrev_b32_e32 v136, 16, v46
	v_and_b32_e32 v137, 0xffff0000, v46
	v_pk_add_f32 v[8:9], v[8:9], v[136:137]
	v_cvt_pk_bf16_f32 v14, v8, v9
	v_lshlrev_b32_e32 v8, 16, v31
	v_and_b32_e32 v9, 0xffff0000, v31
	v_lshlrev_b32_e32 v136, 16, v47
	v_and_b32_e32 v137, 0xffff0000, v47
	v_pk_add_f32 v[8:9], v[8:9], v[136:137]
	v_cvt_pk_bf16_f32 v15, v8, v9
	v_lshlrev_b32_e32 v8, 16, v32
	v_and_b32_e32 v9, 0xffff0000, v32
	v_lshlrev_b32_e32 v136, 16, v48
	v_and_b32_e32 v137, 0xffff0000, v48
	v_pk_add_f32 v[8:9], v[8:9], v[136:137]
	v_cvt_pk_bf16_f32 v16, v8, v9
	v_lshlrev_b32_e32 v8, 16, v33
	v_and_b32_e32 v9, 0xffff0000, v33
	v_lshlrev_b32_e32 v136, 16, v49
	v_and_b32_e32 v137, 0xffff0000, v49
	v_pk_add_f32 v[8:9], v[8:9], v[136:137]
	v_cvt_pk_bf16_f32 v17, v8, v9
	v_lshlrev_b32_e32 v8, 16, v34
	v_and_b32_e32 v9, 0xffff0000, v34
	v_lshlrev_b32_e32 v136, 16, v50
	v_and_b32_e32 v137, 0xffff0000, v50
	v_pk_add_f32 v[8:9], v[8:9], v[136:137]
	v_cvt_pk_bf16_f32 v18, v8, v9
	v_lshlrev_b32_e32 v8, 16, v35
	v_and_b32_e32 v9, 0xffff0000, v35
	v_lshlrev_b32_e32 v136, 16, v51
	v_and_b32_e32 v137, 0xffff0000, v51
	v_pk_add_f32 v[8:9], v[8:9], v[136:137]
	v_cvt_pk_bf16_f32 v19, v8, v9
	v_lshlrev_b32_e32 v8, 16, v36
	v_and_b32_e32 v9, 0xffff0000, v36
	v_lshlrev_b32_e32 v136, 16, v52
	v_and_b32_e32 v137, 0xffff0000, v52
	v_pk_add_f32 v[8:9], v[8:9], v[136:137]
	v_cvt_pk_bf16_f32 v20, v8, v9
	v_lshlrev_b32_e32 v8, 16, v37
	v_and_b32_e32 v9, 0xffff0000, v37
	v_lshlrev_b32_e32 v136, 16, v53
	v_and_b32_e32 v137, 0xffff0000, v53
	v_pk_add_f32 v[8:9], v[8:9], v[136:137]
	v_cvt_pk_bf16_f32 v21, v8, v9
	v_lshlrev_b32_e32 v8, 16, v38
	v_and_b32_e32 v9, 0xffff0000, v38
	v_lshlrev_b32_e32 v136, 16, v54
	v_and_b32_e32 v137, 0xffff0000, v54
	v_pk_add_f32 v[8:9], v[8:9], v[136:137]
	v_cvt_pk_bf16_f32 v22, v8, v9
	v_lshlrev_b32_e32 v8, 16, v39
	v_and_b32_e32 v9, 0xffff0000, v39
	v_lshlrev_b32_e32 v136, 16, v55
	v_and_b32_e32 v137, 0xffff0000, v55
	v_pk_add_f32 v[8:9], v[8:9], v[136:137]
	v_cvt_pk_bf16_f32 v23, v8, v9
	v_lshlrev_b32_e32 v8, 16, v40
	v_and_b32_e32 v9, 0xffff0000, v40
	v_lshlrev_b32_e32 v136, 16, v56
	v_and_b32_e32 v137, 0xffff0000, v56
	v_pk_add_f32 v[8:9], v[8:9], v[136:137]
	v_cvt_pk_bf16_f32 v24, v8, v9
	v_lshlrev_b32_e32 v8, 16, v41
	v_and_b32_e32 v9, 0xffff0000, v41
	v_lshlrev_b32_e32 v136, 16, v57
	v_and_b32_e32 v137, 0xffff0000, v57
	v_pk_add_f32 v[8:9], v[8:9], v[136:137]
	v_cvt_pk_bf16_f32 v25, v8, v9
	s_waitcnt vmcnt(15)
; __device__ __forceinline__ float bf_lo(unsigned w) { return __uint_as_float(w << 16); }
; __device__ __forceinline__ float bf_hi(unsigned w) { return __uint_as_float(w & 0xffff0000u); }
; __device__ __forceinline__ unsigned pk2(float lo, float hi) { return pg8::cvt_pk_bf16(lo, hi); }
; __device__ __forceinline__ void xattn_prompt_item(const bf16_t* xq, const bf16_t* xq1, const bf16_t* memkv, const bf16_t* memvt, bf16_t* xo, int l, int it, int lane) {
;     ...
;     for (int ks = 0; ks < 4; ++ks) {
;         const u32x4 a = *(const u32x4*)(xq + tok * 512 + h * 128 + 32 * ks + 8 * g), c = *(const u32x4*)(xq1 + tok * 512 + h * 128 + 32 * ks + 8 * g);
;         u32x4 w; w.x = pk2(bf_lo(a.x) + bf_lo(c.x), bf_hi(a.x) + bf_hi(c.x)); w.y = pk2(bf_lo(a.y) + bf_lo(c.y), bf_hi(a.y) + bf_hi(c.y));
;         w.z = pk2(bf_lo(a.z) + bf_lo(c.z), bf_hi(a.z) + bf_hi(c.z)); w.w = pk2(bf_lo(a.w) + bf_lo(c.w), bf_hi(a.w) + bf_hi(c.w));
;         qf[ks] = as_bf16x8(w);
;     }
	ds_write_b128 v59, v[146:149] offset:0
	s_waitcnt vmcnt(14)
	ds_write_b128 v59, v[150:153] offset:8704
	s_waitcnt vmcnt(13)
	ds_write_b128 v59, v[154:157] offset:17408
	s_waitcnt vmcnt(12)
	ds_write_b128 v59, v[158:161] offset:26112
	s_waitcnt vmcnt(11)
	ds_write_b128 v59, v[162:165] offset:34816
	s_waitcnt vmcnt(10)
	ds_write_b128 v59, v[166:169] offset:43520
	s_waitcnt vmcnt(9)
	ds_write_b128 v59, v[170:173] offset:52224
	s_waitcnt vmcnt(8)
	ds_write_b128 v59, v[174:177] offset:60928
	s_waitcnt vmcnt(7)
	ds_write_b128 v61, v[178:181] offset:0
	s_waitcnt vmcnt(6)
	ds_write_b128 v61, v[182:185] offset:8448
	s_waitcnt vmcnt(5)
	ds_write_b128 v61, v[186:189] offset:16896
	s_waitcnt vmcnt(4)
	ds_write_b128 v61, v[190:193] offset:25344
	s_waitcnt vmcnt(3)
	ds_write_b128 v61, v[194:197] offset:33792
	s_waitcnt vmcnt(2)
	ds_write_b128 v61, v[198:201] offset:42240
	s_waitcnt vmcnt(1)
	ds_write_b128 v61, v[202:205] offset:50688
	s_waitcnt vmcnt(0)
	ds_write_b128 v61, v[206:209] offset:59136
	s_waitcnt lgkmcnt(0)
	s_barrier
	s_branch .Lxp_go
.Lxp_nostage:
	s_add_u32 s4, s14, s4
	s_addc_u32 s5, s15, 0
	s_waitcnt vmcnt(0)
	v_lshlrev_b32_e32 v8, 16, v96
	v_and_b32_e32 v9, 0xffff0000, v96
	v_lshlrev_b32_e32 v136, 16, v112
	v_and_b32_e32 v137, 0xffff0000, v112
	v_pk_add_f32 v[8:9], v[8:9], v[136:137]
	v_cvt_pk_bf16_f32 v10, v8, v9
	v_lshlrev_b32_e32 v8, 16, v97
	v_and_b32_e32 v9, 0xffff0000, v97
	v_lshlrev_b32_e32 v136, 16, v113
	v_and_b32_e32 v137, 0xffff0000, v113
	v_pk_add_f32 v[8:9], v[8:9], v[136:137]
	v_cvt_pk_bf16_f32 v11, v8, v9
	v_lshlrev_b32_e32 v8, 16, v98
	v_and_b32_e32 v9, 0xffff0000, v98
	v_lshlrev_b32_e32 v136, 16, v114
	v_and_b32_e32 v137, 0xffff0000, v114
	v_pk_add_f32 v[8:9], v[8:9], v[136:137]
	v_cvt_pk_bf16_f32 v12, v8, v9
	v_lshlrev_b32_e32 v8, 16, v99
	v_and_b32_e32 v9, 0xffff0000, v99
	v_lshlrev_b32_e32 v136, 16, v115
	v_and_b32_e32 v137, 0xffff0000, v115
	v_pk_add_f32 v[8:9], v[8:9], v[136:137]
	v_cvt_pk_bf16_f32 v13, v8, v9
	v_lshlrev_b32_e32 v8, 16, v100
	v_and_b32_e32 v9, 0xffff0000, v100
	v_lshlrev_b32_e32 v136, 16, v116
	v_and_b32_e32 v137, 0xffff0000, v116
	v_pk_add_f32 v[8:9], v[8:9], v[136:137]
	v_cvt_pk_bf16_f32 v14, v8, v9
	v_lshlrev_b32_e32 v8, 16, v101
	v_and_b32_e32 v9, 0xffff0000, v101
	v_lshlrev_b32_e32 v136, 16, v117
	v_and_b32_e32 v137, 0xffff0000, v117
	v_pk_add_f32 v[8:9], v[8:9], v[136:137]
	v_cvt_pk_bf16_f32 v15, v8, v9
	v_lshlrev_b32_e32 v8, 16, v102
	v_and_b32_e32 v9, 0xffff0000, v102
	v_lshlrev_b32_e32 v136, 16, v118
	v_and_b32_e32 v137, 0xffff0000, v118
	v_pk_add_f32 v[8:9], v[8:9], v[136:137]
	v_cvt_pk_bf16_f32 v16, v8, v9
	v_lshlrev_b32_e32 v8, 16, v103
	v_and_b32_e32 v9, 0xffff0000, v103
	v_lshlrev_b32_e32 v136, 16, v119
	v_and_b32_e32 v137, 0xffff0000, v119
	v_pk_add_f32 v[8:9], v[8:9], v[136:137]
	v_cvt_pk_bf16_f32 v17, v8, v9
	v_lshlrev_b32_e32 v8, 16, v104
	v_and_b32_e32 v9, 0xffff0000, v104
	v_lshlrev_b32_e32 v136, 16, v120
	v_and_b32_e32 v137, 0xffff0000, v120
	v_pk_add_f32 v[8:9], v[8:9], v[136:137]
	v_cvt_pk_bf16_f32 v18, v8, v9
	v_lshlrev_b32_e32 v8, 16, v105
	v_and_b32_e32 v9, 0xffff0000, v105
	v_lshlrev_b32_e32 v136, 16, v121
	v_and_b32_e32 v137, 0xffff0000, v121
	v_pk_add_f32 v[8:9], v[8:9], v[136:137]
	v_cvt_pk_bf16_f32 v19, v8, v9
	v_lshlrev_b32_e32 v8, 16, v106
	v_and_b32_e32 v9, 0xffff0000, v106
	v_lshlrev_b32_e32 v136, 16, v122
	v_and_b32_e32 v137, 0xffff0000, v122
	v_pk_add_f32 v[8:9], v[8:9], v[136:137]
	v_cvt_pk_bf16_f32 v20, v8, v9
	v_lshlrev_b32_e32 v8, 16, v107
	v_and_b32_e32 v9, 0xffff0000, v107
	v_lshlrev_b32_e32 v136, 16, v123
	v_and_b32_e32 v137, 0xffff0000, v123
	v_pk_add_f32 v[8:9], v[8:9], v[136:137]
	v_cvt_pk_bf16_f32 v21, v8, v9
	v_lshlrev_b32_e32 v8, 16, v108
	v_and_b32_e32 v9, 0xffff0000, v108
	v_lshlrev_b32_e32 v136, 16, v124
	v_and_b32_e32 v137, 0xffff0000, v124
	v_pk_add_f32 v[8:9], v[8:9], v[136:137]
	v_cvt_pk_bf16_f32 v22, v8, v9
	v_lshlrev_b32_e32 v8, 16, v109
	v_and_b32_e32 v9, 0xffff0000, v109
	v_lshlrev_b32_e32 v136, 16, v125
	v_and_b32_e32 v137, 0xffff0000, v125
	v_pk_add_f32 v[8:9], v[8:9], v[136:137]
	v_cvt_pk_bf16_f32 v23, v8, v9
	v_lshlrev_b32_e32 v8, 16, v110
	v_and_b32_e32 v9, 0xffff0000, v110
	v_lshlrev_b32_e32 v136, 16, v126
	v_and_b32_e32 v137, 0xffff0000, v126
	v_pk_add_f32 v[8:9], v[8:9], v[136:137]
	v_cvt_pk_bf16_f32 v24, v8, v9
	v_lshlrev_b32_e32 v8, 16, v111
	v_and_b32_e32 v9, 0xffff0000, v111
	v_lshlrev_b32_e32 v136, 16, v127
	v_and_b32_e32 v137, 0xffff0000, v127
	v_pk_add_f32 v[8:9], v[8:9], v[136:137]
	v_cvt_pk_bf16_f32 v25, v8, v9
; #define MFMA16(a, b, c) __builtin_amdgcn_mfma_f32_16x16x32_bf16((a), (b), (c), 0, 0, 0)
; __device__ __forceinline__ void xattn_prompt_item(const bf16_t* xq, const bf16_t* xq1, const bf16_t* memkv, const bf16_t* memvt, bf16_t* xo, int l, int it, int lane) {
;     ...
; #pragma unroll
;     for (int kt = 0; kt < 16; ++kt) {
;         const bf16_t* kp = memkv + ((size_t)b * 256 + 16 * kt + l15) * 4096 + l * 1024 + h * 128 + 8 * g;
;         f32x4 a = {0.f, 0.f, 0.f, 0.f};
; #pragma unroll
;         for (int ks = 0; ks < 4; ++ks) a = MFMA16(*(const bf16x8*)(kp + 32 * ks), qf[ks], a);
;         a = a * 0.08838834764831845f;
;         sc[kt] = a; mx = fmaxf(fmaxf(mx, fmaxf(a[0], a[1])), fmaxf(a[2], a[3]));
;     }
.Lxp_go:
	v_mov_b32_e32 v63, 0xf149f2ca
	ds_read_b128 v[146:149], v3 offset:0
	ds_read_b128 v[150:153], v3 offset:64
	ds_read_b128 v[154:157], v3 offset:128
	ds_read_b128 v[158:161], v3 offset:192
	ds_read_b128 v[162:165], v3 offset:4352
	ds_read_b128 v[166:169], v3 offset:4416
	ds_read_b128 v[170:173], v3 offset:4480
	ds_read_b128 v[174:177], v3 offset:4544
	ds_read_b128 v[178:181], v3 offset:8704
	ds_read_b128 v[182:185], v3 offset:8768
	ds_read_b128 v[186:189], v3 offset:8832
	ds_read_b128 v[190:193], v3 offset:8896
	s_waitcnt lgkmcnt(4)
	v_mfma_f32_16x16x32_bf16 v[64:67], v[146:149], v[10:13], 0
	v_mfma_f32_16x16x32_bf16 v[68:71], v[162:165], v[10:13], 0
	ds_read_b128 v[194:197], v3 offset:13056
	v_mfma_f32_16x16x32_bf16 v[64:67], v[150:153], v[14:17], v[64:67]
	v_mfma_f32_16x16x32_bf16 v[68:71], v[166:169], v[14:17], v[68:71]
	ds_read_b128 v[198:201], v3 offset:13120
	v_mfma_f32_16x16x32_bf16 v[64:67], v[154:157], v[18:21], v[64:67]
	v_mfma_f32_16x16x32_bf16 v[68:71], v[170:173], v[18:21], v[68:71]
	ds_read_b128 v[202:205], v3 offset:13184
	v_mfma_f32_16x16x32_bf16 v[64:67], v[158:161], v[22:25], v[64:67]
	v_mfma_f32_16x16x32_bf16 v[68:71], v[174:177], v[22:25], v[68:71]
	ds_read_b128 v[206:209], v3 offset:13248
	ds_read_b128 v[146:149], v3 offset:17408
	ds_read_b128 v[150:153], v3 offset:17472
	ds_read_b128 v[154:157], v3 offset:17536
	ds_read_b128 v[158:161], v3 offset:17600
	s_waitcnt lgkmcnt(4)
	v_mfma_f32_16x16x32_bf16 v[72:75], v[178:181], v[10:13], 0
	v_mfma_f32_16x16x32_bf16 v[76:79], v[194:197], v[10:13], 0
	ds_read_b128 v[162:165], v3 offset:21760
	v_mfma_f32_16x16x32_bf16 v[72:75], v[182:185], v[14:17], v[72:75]
	v_mfma_f32_16x16x32_bf16 v[76:79], v[198:201], v[14:17], v[76:79]
	ds_read_b128 v[166:169], v3 offset:21824
	v_mfma_f32_16x16x32_bf16 v[72:75], v[186:189], v[18:21], v[72:75]
	v_mfma_f32_16x16x32_bf16 v[76:79], v[202:205], v[18:21], v[76:79]
	ds_read_b128 v[170:173], v3 offset:21888
	v_mfma_f32_16x16x32_bf16 v[72:75], v[190:193], v[22:25], v[72:75]
	v_mfma_f32_16x16x32_bf16 v[76:79], v[206:209], v[22:25], v[76:79]
	ds_read_b128 v[174:177], v3 offset:21952
	v_pk_mul_f32 v[64:65], v[64:65], s[86:87] op_sel_hi:[1,0]
	v_pk_mul_f32 v[66:67], v[66:67], s[86:87] op_sel_hi:[1,0]
	v_max3_f32 v63, v63, v64, v65
	v_max3_f32 v63, v63, v66, v67
	v_pk_mul_f32 v[68:69], v[68:69], s[86:87] op_sel_hi:[1,0]
	v_pk_mul_f32 v[70:71], v[70:71], s[86:87] op_sel_hi:[1,0]
	v_max3_f32 v63, v63, v68, v69
	v_max3_f32 v63, v63, v70, v71
	ds_read_b128 v[178:181], v3 offset:26112
	ds_read_b128 v[182:185], v3 offset:26176
	ds_read_b128 v[186:189], v3 offset:26240
	ds_read_b128 v[190:193], v3 offset:26304
	s_waitcnt lgkmcnt(4)
	v_mfma_f32_16x16x32_bf16 v[80:83], v[146:149], v[10:13], 0
	v_mfma_f32_16x16x32_bf16 v[84:87], v[162:165], v[10:13], 0
	ds_read_b128 v[194:197], v3 offset:30464
	v_mfma_f32_16x16x32_bf16 v[80:83], v[150:153], v[14:17], v[80:83]
	v_mfma_f32_16x16x32_bf16 v[84:87], v[166:169], v[14:17], v[84:87]
	ds_read_b128 v[198:201], v3 offset:30528
	v_mfma_f32_16x16x32_bf16 v[80:83], v[154:157], v[18:21], v[80:83]
	v_mfma_f32_16x16x32_bf16 v[84:87], v[170:173], v[18:21], v[84:87]
	ds_read_b128 v[202:205], v3 offset:30592
	v_mfma_f32_16x16x32_bf16 v[80:83], v[158:161], v[22:25], v[80:83]
	v_mfma_f32_16x16x32_bf16 v[84:87], v[174:177], v[22:25], v[84:87]
	ds_read_b128 v[206:209], v3 offset:30656
	v_pk_mul_f32 v[72:73], v[72:73], s[86:87] op_sel_hi:[1,0]
	v_pk_mul_f32 v[74:75], v[74:75], s[86:87] op_sel_hi:[1,0]
	v_max3_f32 v63, v63, v72, v73
	v_max3_f32 v63, v63, v74, v75
	v_pk_mul_f32 v[76:77], v[76:77], s[86:87] op_sel_hi:[1,0]
	v_pk_mul_f32 v[78:79], v[78:79], s[86:87] op_sel_hi:[1,0]
	v_max3_f32 v63, v63, v76, v77
	v_max3_f32 v63, v63, v78, v79
	ds_read_b128 v[146:149], v3 offset:34816
	ds_read_b128 v[150:153], v3 offset:34880
	ds_read_b128 v[154:157], v3 offset:34944
	ds_read_b128 v[158:161], v3 offset:35008
	s_waitcnt lgkmcnt(4)
	v_mfma_f32_16x16x32_bf16 v[88:91], v[178:181], v[10:13], 0
	v_mfma_f32_16x16x32_bf16 v[92:95], v[194:197], v[10:13], 0
	ds_read_b128 v[162:165], v3 offset:39168
	v_mfma_f32_16x16x32_bf16 v[88:91], v[182:185], v[14:17], v[88:91]
	v_mfma_f32_16x16x32_bf16 v[92:95], v[198:201], v[14:17], v[92:95]
	ds_read_b128 v[166:169], v3 offset:39232
	v_mfma_f32_16x16x32_bf16 v[88:91], v[186:189], v[18:21], v[88:91]
	v_mfma_f32_16x16x32_bf16 v[92:95], v[202:205], v[18:21], v[92:95]
	ds_read_b128 v[170:173], v3 offset:39296
	v_mfma_f32_16x16x32_bf16 v[88:91], v[190:193], v[22:25], v[88:91]
	v_mfma_f32_16x16x32_bf16 v[92:95], v[206:209], v[22:25], v[92:95]
	ds_read_b128 v[174:177], v3 offset:39360
	v_pk_mul_f32 v[80:81], v[80:81], s[86:87] op_sel_hi:[1,0]
	v_pk_mul_f32 v[82:83], v[82:83], s[86:87] op_sel_hi:[1,0]
	v_max3_f32 v63, v63, v80, v81
	v_max3_f32 v63, v63, v82, v83
	v_pk_mul_f32 v[84:85], v[84:85], s[86:87] op_sel_hi:[1,0]
	v_pk_mul_f32 v[86:87], v[86:87], s[86:87] op_sel_hi:[1,0]
	v_max3_f32 v63, v63, v84, v85
	v_max3_f32 v63, v63, v86, v87
	ds_read_b128 v[178:181], v3 offset:43520
	ds_read_b128 v[182:185], v3 offset:43584
	ds_read_b128 v[186:189], v3 offset:43648
	ds_read_b128 v[190:193], v3 offset:43712
	s_waitcnt lgkmcnt(4)
; #define MFMA16(a, b, c) __builtin_amdgcn_mfma_f32_16x16x32_bf16((a), (b), (c), 0, 0, 0)
; __device__ __forceinline__ void xattn_prompt_item(const bf16_t* xq, const bf16_t* xq1, const bf16_t* memkv, const bf16_t* memvt, bf16_t* xo, int l, int it, int lane) {
;     ...
; #pragma unroll
;     for (int kt = 0; kt < 16; ++kt) {
;         const bf16_t* kp = memkv + ((size_t)b * 256 + 16 * kt + l15) * 4096 + l * 1024 + h * 128 + 8 * g;
;         f32x4 a = {0.f, 0.f, 0.f, 0.f};
; #pragma unroll
;         for (int ks = 0; ks < 4; ++ks) a = MFMA16(*(const bf16x8*)(kp + 32 * ks), qf[ks], a);
;         a = a * 0.08838834764831845f;
;         sc[kt] = a; mx = fmaxf(fmaxf(mx, fmaxf(a[0], a[1])), fmaxf(a[2], a[3]));
;     }
;     mx = fmaxf(mx, __shfl_xor(mx, 16)); mx = fmaxf(mx, __shfl_xor(mx, 32));
	v_mfma_f32_16x16x32_bf16 v[96:99], v[146:149], v[10:13], 0
	v_mfma_f32_16x16x32_bf16 v[100:103], v[162:165], v[10:13], 0
	ds_read_b128 v[194:197], v3 offset:47872
	v_mfma_f32_16x16x32_bf16 v[96:99], v[150:153], v[14:17], v[96:99]
	v_mfma_f32_16x16x32_bf16 v[100:103], v[166:169], v[14:17], v[100:103]
	ds_read_b128 v[198:201], v3 offset:47936
	v_mfma_f32_16x16x32_bf16 v[96:99], v[154:157], v[18:21], v[96:99]
	v_mfma_f32_16x16x32_bf16 v[100:103], v[170:173], v[18:21], v[100:103]
	ds_read_b128 v[202:205], v3 offset:48000
	v_mfma_f32_16x16x32_bf16 v[96:99], v[158:161], v[22:25], v[96:99]
	v_mfma_f32_16x16x32_bf16 v[100:103], v[174:177], v[22:25], v[100:103]
	ds_read_b128 v[206:209], v3 offset:48064
	v_pk_mul_f32 v[88:89], v[88:89], s[86:87] op_sel_hi:[1,0]
	v_pk_mul_f32 v[90:91], v[90:91], s[86:87] op_sel_hi:[1,0]
	v_max3_f32 v63, v63, v88, v89
	v_max3_f32 v63, v63, v90, v91
	v_pk_mul_f32 v[92:93], v[92:93], s[86:87] op_sel_hi:[1,0]
	v_pk_mul_f32 v[94:95], v[94:95], s[86:87] op_sel_hi:[1,0]
	v_max3_f32 v63, v63, v92, v93
	v_max3_f32 v63, v63, v94, v95
	ds_read_b128 v[146:149], v3 offset:52224
	ds_read_b128 v[150:153], v3 offset:52288
	ds_read_b128 v[154:157], v3 offset:52352
	ds_read_b128 v[158:161], v3 offset:52416
	s_waitcnt lgkmcnt(4)
	v_mfma_f32_16x16x32_bf16 v[104:107], v[178:181], v[10:13], 0
	v_mfma_f32_16x16x32_bf16 v[108:111], v[194:197], v[10:13], 0
	ds_read_b128 v[162:165], v3 offset:56576
	v_mfma_f32_16x16x32_bf16 v[104:107], v[182:185], v[14:17], v[104:107]
	v_mfma_f32_16x16x32_bf16 v[108:111], v[198:201], v[14:17], v[108:111]
	ds_read_b128 v[166:169], v3 offset:56640
	v_mfma_f32_16x16x32_bf16 v[104:107], v[186:189], v[18:21], v[104:107]
	v_mfma_f32_16x16x32_bf16 v[108:111], v[202:205], v[18:21], v[108:111]
	ds_read_b128 v[170:173], v3 offset:56704
	v_mfma_f32_16x16x32_bf16 v[104:107], v[190:193], v[22:25], v[104:107]
	v_mfma_f32_16x16x32_bf16 v[108:111], v[206:209], v[22:25], v[108:111]
	ds_read_b128 v[174:177], v3 offset:56768
	v_pk_mul_f32 v[96:97], v[96:97], s[86:87] op_sel_hi:[1,0]
	v_pk_mul_f32 v[98:99], v[98:99], s[86:87] op_sel_hi:[1,0]
	v_max3_f32 v63, v63, v96, v97
	v_max3_f32 v63, v63, v98, v99
	v_pk_mul_f32 v[100:101], v[100:101], s[86:87] op_sel_hi:[1,0]
	v_pk_mul_f32 v[102:103], v[102:103], s[86:87] op_sel_hi:[1,0]
	v_max3_f32 v63, v63, v100, v101
	v_max3_f32 v63, v63, v102, v103
	ds_read_b128 v[178:181], v3 offset:60928
	ds_read_b128 v[182:185], v3 offset:60992
	ds_read_b128 v[186:189], v3 offset:61056
	ds_read_b128 v[190:193], v3 offset:61120
	s_waitcnt lgkmcnt(4)
	v_mfma_f32_16x16x32_bf16 v[112:115], v[146:149], v[10:13], 0
	v_mfma_f32_16x16x32_bf16 v[116:119], v[162:165], v[10:13], 0
	ds_read_b128 v[194:197], v3 offset:65280
	v_mfma_f32_16x16x32_bf16 v[112:115], v[150:153], v[14:17], v[112:115]
	v_mfma_f32_16x16x32_bf16 v[116:119], v[166:169], v[14:17], v[116:119]
	ds_read_b128 v[198:201], v3 offset:65344
	v_mfma_f32_16x16x32_bf16 v[112:115], v[154:157], v[18:21], v[112:115]
	v_mfma_f32_16x16x32_bf16 v[116:119], v[170:173], v[18:21], v[116:119]
	ds_read_b128 v[202:205], v3 offset:65408
	v_mfma_f32_16x16x32_bf16 v[112:115], v[158:161], v[22:25], v[112:115]
	v_mfma_f32_16x16x32_bf16 v[116:119], v[174:177], v[22:25], v[116:119]
	ds_read_b128 v[206:209], v3 offset:65472
	v_pk_mul_f32 v[104:105], v[104:105], s[86:87] op_sel_hi:[1,0]
	v_pk_mul_f32 v[106:107], v[106:107], s[86:87] op_sel_hi:[1,0]
	v_max3_f32 v63, v63, v104, v105
	v_max3_f32 v63, v63, v106, v107
	v_pk_mul_f32 v[108:109], v[108:109], s[86:87] op_sel_hi:[1,0]
	v_pk_mul_f32 v[110:111], v[110:111], s[86:87] op_sel_hi:[1,0]
	v_max3_f32 v63, v63, v108, v109
	v_max3_f32 v63, v63, v110, v111
	ds_read_b128 v[146:149], v4 offset:0
	ds_read_b128 v[150:153], v4 offset:8448
	ds_read_b128 v[154:157], v4 offset:16896
	ds_read_b128 v[158:161], v4 offset:25344
	s_waitcnt lgkmcnt(4)
	v_mfma_f32_16x16x32_bf16 v[120:123], v[178:181], v[10:13], 0
	v_mfma_f32_16x16x32_bf16 v[124:127], v[194:197], v[10:13], 0
	ds_read_b128 v[162:165], v4 offset:33792
	v_mfma_f32_16x16x32_bf16 v[120:123], v[182:185], v[14:17], v[120:123]
	v_mfma_f32_16x16x32_bf16 v[124:127], v[198:201], v[14:17], v[124:127]
	ds_read_b128 v[166:169], v4 offset:42240
	v_mfma_f32_16x16x32_bf16 v[120:123], v[186:189], v[18:21], v[120:123]
	v_mfma_f32_16x16x32_bf16 v[124:127], v[202:205], v[18:21], v[124:127]
	ds_read_b128 v[170:173], v4 offset:50688
	v_mfma_f32_16x16x32_bf16 v[120:123], v[190:193], v[22:25], v[120:123]
	v_mfma_f32_16x16x32_bf16 v[124:127], v[206:209], v[22:25], v[124:127]
	ds_read_b128 v[174:177], v4 offset:59136
	v_pk_mul_f32 v[112:113], v[112:113], s[86:87] op_sel_hi:[1,0]
	v_pk_mul_f32 v[114:115], v[114:115], s[86:87] op_sel_hi:[1,0]
	v_max3_f32 v63, v63, v112, v113
	v_max3_f32 v63, v63, v114, v115
	v_pk_mul_f32 v[116:117], v[116:117], s[86:87] op_sel_hi:[1,0]
	v_pk_mul_f32 v[118:119], v[118:119], s[86:87] op_sel_hi:[1,0]
	v_max3_f32 v63, v63, v116, v117
	v_max3_f32 v63, v63, v118, v119
	s_nop 7
	v_pk_mul_f32 v[120:121], v[120:121], s[86:87] op_sel_hi:[1,0]
	v_pk_mul_f32 v[122:123], v[122:123], s[86:87] op_sel_hi:[1,0]
	v_max3_f32 v63, v63, v120, v121
	v_max3_f32 v63, v63, v122, v123
	v_pk_mul_f32 v[124:125], v[124:125], s[86:87] op_sel_hi:[1,0]
	v_pk_mul_f32 v[126:127], v[126:127], s[86:87] op_sel_hi:[1,0]
	v_max3_f32 v63, v63, v124, v125
	v_max3_f32 v63, v63, v126, v127
	ds_bpermute_b32 v8, v6, v63
	s_waitcnt lgkmcnt(0)
	v_max_f32_e32 v8, v8, v8
	v_max_f32_e32 v63, v63, v8
	ds_bpermute_b32 v8, v7, v63
	s_waitcnt lgkmcnt(0)
; __device__ __forceinline__ void xattn_prompt_item(const bf16_t* xq, const bf16_t* xq1, const bf16_t* memkv, const bf16_t* memvt, bf16_t* xo, int l, int it, int lane) {
;     ...
;     float sum = 0.f;
; #pragma unroll
;     for (int kt = 0; kt < 16; ++kt)
; #pragma unroll
;         for (int j = 0; j < 4; ++j) { const float p = __expf(sc[kt][j] - mx); sc[kt][j] = p; sum += p; }
	v_max_f32_e32 v8, v8, v8
	v_max_f32_e32 v63, v63, v8
	v_mov_b32_e32 v62, 0
	v_sub_f32_e32 v64, v64, v63
	v_mul_f32_e32 v64, 0x3fb8aa3b, v64
	v_exp_f32_e32 v64, v64
	v_sub_f32_e32 v65, v65, v63
	v_mul_f32_e32 v65, 0x3fb8aa3b, v65
	v_exp_f32_e32 v65, v65
	v_add_f32_e32 v62, v64, v62
	v_sub_f32_e32 v66, v66, v63
	v_mul_f32_e32 v66, 0x3fb8aa3b, v66
	v_exp_f32_e32 v66, v66
	v_add_f32_e32 v62, v65, v62
	v_sub_f32_e32 v67, v67, v63
	v_mul_f32_e32 v67, 0x3fb8aa3b, v67
	v_exp_f32_e32 v67, v67
	v_add_f32_e32 v62, v66, v62
	v_sub_f32_e32 v68, v68, v63
	v_mul_f32_e32 v68, 0x3fb8aa3b, v68
	v_exp_f32_e32 v68, v68
	v_add_f32_e32 v62, v67, v62
	v_sub_f32_e32 v69, v69, v63
	v_mul_f32_e32 v69, 0x3fb8aa3b, v69
	v_exp_f32_e32 v69, v69
	v_add_f32_e32 v62, v68, v62
	v_sub_f32_e32 v70, v70, v63
	v_mul_f32_e32 v70, 0x3fb8aa3b, v70
	v_exp_f32_e32 v70, v70
	v_add_f32_e32 v62, v69, v62
	v_sub_f32_e32 v71, v71, v63
	v_mul_f32_e32 v71, 0x3fb8aa3b, v71
	v_exp_f32_e32 v71, v71
	v_add_f32_e32 v62, v70, v62
	v_sub_f32_e32 v72, v72, v63
	v_mul_f32_e32 v72, 0x3fb8aa3b, v72
	v_exp_f32_e32 v72, v72
	v_add_f32_e32 v62, v71, v62
	v_sub_f32_e32 v73, v73, v63
	v_mul_f32_e32 v73, 0x3fb8aa3b, v73
	v_exp_f32_e32 v73, v73
	v_add_f32_e32 v62, v72, v62
	v_sub_f32_e32 v74, v74, v63
	v_mul_f32_e32 v74, 0x3fb8aa3b, v74
	v_exp_f32_e32 v74, v74
	v_add_f32_e32 v62, v73, v62
	v_sub_f32_e32 v75, v75, v63
	v_mul_f32_e32 v75, 0x3fb8aa3b, v75
	v_exp_f32_e32 v75, v75
	v_add_f32_e32 v62, v74, v62
	v_sub_f32_e32 v76, v76, v63
	v_mul_f32_e32 v76, 0x3fb8aa3b, v76
	v_exp_f32_e32 v76, v76
	v_add_f32_e32 v62, v75, v62
	v_sub_f32_e32 v77, v77, v63
	v_mul_f32_e32 v77, 0x3fb8aa3b, v77
	v_exp_f32_e32 v77, v77
	v_add_f32_e32 v62, v76, v62
	v_sub_f32_e32 v78, v78, v63
	v_mul_f32_e32 v78, 0x3fb8aa3b, v78
	v_exp_f32_e32 v78, v78
	v_add_f32_e32 v62, v77, v62
	v_sub_f32_e32 v79, v79, v63
	v_mul_f32_e32 v79, 0x3fb8aa3b, v79
	v_exp_f32_e32 v79, v79
	v_add_f32_e32 v62, v78, v62
	v_sub_f32_e32 v80, v80, v63
	v_mul_f32_e32 v80, 0x3fb8aa3b, v80
	v_exp_f32_e32 v80, v80
	v_add_f32_e32 v62, v79, v62
	v_sub_f32_e32 v81, v81, v63
	v_mul_f32_e32 v81, 0x3fb8aa3b, v81
	v_exp_f32_e32 v81, v81
	v_add_f32_e32 v62, v80, v62
	v_sub_f32_e32 v82, v82, v63
	v_mul_f32_e32 v82, 0x3fb8aa3b, v82
	v_exp_f32_e32 v82, v82
	v_add_f32_e32 v62, v81, v62
	v_sub_f32_e32 v83, v83, v63
	v_mul_f32_e32 v83, 0x3fb8aa3b, v83
	v_exp_f32_e32 v83, v83
	v_add_f32_e32 v62, v82, v62
	v_sub_f32_e32 v84, v84, v63
	v_mul_f32_e32 v84, 0x3fb8aa3b, v84
	v_exp_f32_e32 v84, v84
	v_add_f32_e32 v62, v83, v62
	v_sub_f32_e32 v85, v85, v63
	v_mul_f32_e32 v85, 0x3fb8aa3b, v85
	v_exp_f32_e32 v85, v85
	v_add_f32_e32 v62, v84, v62
	v_sub_f32_e32 v86, v86, v63
	v_mul_f32_e32 v86, 0x3fb8aa3b, v86
	v_exp_f32_e32 v86, v86
	v_add_f32_e32 v62, v85, v62
	v_sub_f32_e32 v87, v87, v63
	v_mul_f32_e32 v87, 0x3fb8aa3b, v87
	v_exp_f32_e32 v87, v87
	v_add_f32_e32 v62, v86, v62
	v_sub_f32_e32 v88, v88, v63
	v_mul_f32_e32 v88, 0x3fb8aa3b, v88
	v_exp_f32_e32 v88, v88
	v_add_f32_e32 v62, v87, v62
	v_sub_f32_e32 v89, v89, v63
	v_mul_f32_e32 v89, 0x3fb8aa3b, v89
	v_exp_f32_e32 v89, v89
	v_add_f32_e32 v62, v88, v62
	v_sub_f32_e32 v90, v90, v63
	v_mul_f32_e32 v90, 0x3fb8aa3b, v90
	v_exp_f32_e32 v90, v90
	v_add_f32_e32 v62, v89, v62
	v_sub_f32_e32 v91, v91, v63
	v_mul_f32_e32 v91, 0x3fb8aa3b, v91
	v_exp_f32_e32 v91, v91
	v_add_f32_e32 v62, v90, v62
	v_sub_f32_e32 v92, v92, v63
	v_mul_f32_e32 v92, 0x3fb8aa3b, v92
	v_exp_f32_e32 v92, v92
	v_add_f32_e32 v62, v91, v62
	v_sub_f32_e32 v93, v93, v63
	v_mul_f32_e32 v93, 0x3fb8aa3b, v93
	v_exp_f32_e32 v93, v93
	v_add_f32_e32 v62, v92, v62
	v_sub_f32_e32 v94, v94, v63
	v_mul_f32_e32 v94, 0x3fb8aa3b, v94
	v_exp_f32_e32 v94, v94
	v_add_f32_e32 v62, v93, v62
	v_sub_f32_e32 v95, v95, v63
	v_mul_f32_e32 v95, 0x3fb8aa3b, v95
	v_exp_f32_e32 v95, v95
	v_add_f32_e32 v62, v94, v62
	v_sub_f32_e32 v96, v96, v63
	v_mul_f32_e32 v96, 0x3fb8aa3b, v96
	v_exp_f32_e32 v96, v96
	v_add_f32_e32 v62, v95, v62
	v_sub_f32_e32 v97, v97, v63
	v_mul_f32_e32 v97, 0x3fb8aa3b, v97
	v_exp_f32_e32 v97, v97
	v_add_f32_e32 v62, v96, v62
	v_sub_f32_e32 v98, v98, v63
	v_mul_f32_e32 v98, 0x3fb8aa3b, v98
	v_exp_f32_e32 v98, v98
	v_add_f32_e32 v62, v97, v62
	v_sub_f32_e32 v99, v99, v63
	v_mul_f32_e32 v99, 0x3fb8aa3b, v99
	v_exp_f32_e32 v99, v99
	v_add_f32_e32 v62, v98, v62
	v_sub_f32_e32 v100, v100, v63
	v_mul_f32_e32 v100, 0x3fb8aa3b, v100
	v_exp_f32_e32 v100, v100
	v_add_f32_e32 v62, v99, v62
	v_sub_f32_e32 v101, v101, v63
	v_mul_f32_e32 v101, 0x3fb8aa3b, v101
	v_exp_f32_e32 v101, v101
	v_add_f32_e32 v62, v100, v62
	v_sub_f32_e32 v102, v102, v63
	v_mul_f32_e32 v102, 0x3fb8aa3b, v102
	v_exp_f32_e32 v102, v102
	v_add_f32_e32 v62, v101, v62
	v_sub_f32_e32 v103, v103, v63
	v_mul_f32_e32 v103, 0x3fb8aa3b, v103
	v_exp_f32_e32 v103, v103
	v_add_f32_e32 v62, v102, v62
	v_sub_f32_e32 v104, v104, v63
	v_mul_f32_e32 v104, 0x3fb8aa3b, v104
	v_exp_f32_e32 v104, v104
	v_add_f32_e32 v62, v103, v62
	v_sub_f32_e32 v105, v105, v63
	v_mul_f32_e32 v105, 0x3fb8aa3b, v105
	v_exp_f32_e32 v105, v105
	v_add_f32_e32 v62, v104, v62
	v_sub_f32_e32 v106, v106, v63
	v_mul_f32_e32 v106, 0x3fb8aa3b, v106
	v_exp_f32_e32 v106, v106
	v_add_f32_e32 v62, v105, v62
	v_sub_f32_e32 v107, v107, v63
	v_mul_f32_e32 v107, 0x3fb8aa3b, v107
	v_exp_f32_e32 v107, v107
	v_add_f32_e32 v62, v106, v62
	v_sub_f32_e32 v108, v108, v63
	v_mul_f32_e32 v108, 0x3fb8aa3b, v108
	v_exp_f32_e32 v108, v108
	v_add_f32_e32 v62, v107, v62
	v_sub_f32_e32 v109, v109, v63
	v_mul_f32_e32 v109, 0x3fb8aa3b, v109
	v_exp_f32_e32 v109, v109
	v_add_f32_e32 v62, v108, v62
	v_sub_f32_e32 v110, v110, v63
	v_mul_f32_e32 v110, 0x3fb8aa3b, v110
	v_exp_f32_e32 v110, v110
; __device__ __forceinline__ unsigned pk2(float lo, float hi) { return pg8::cvt_pk_bf16(lo, hi); }
; __device__ __forceinline__ void xattn_prompt_item(const bf16_t* xq, const bf16_t* xq1, const bf16_t* memkv, const bf16_t* memvt, bf16_t* xo, int l, int it, int lane) {
;     ...
;         for (int j = 0; j < 4; ++j) { const float p = __expf(sc[kt][j] - mx); sc[kt][j] = p; sum += p; }
;     sum += __shfl_xor(sum, 16); sum += __shfl_xor(sum, 32);
;     const float inv = 1.0f / sum;
;     f32x4 o[8];
; #pragma unroll
;     for (int mi = 0; mi < 8; ++mi) o[mi] = (f32x4){0.f, 0.f, 0.f, 0.f};
; #pragma unroll
;     for (int u = 0; u < 8; ++u) {
;         u32x4 pw; pw.x = pk2(sc[2 * u][0] * inv, sc[2 * u][1] * inv); pw.y = pk2(sc[2 * u][2] * inv, sc[2 * u][3] * inv);
;         pw.z = pk2(sc[2 * u + 1][0] * inv, sc[2 * u + 1][1] * inv); pw.w = pk2(sc[2 * u + 1][2] * inv, sc[2 * u + 1][3] * inv);
;         const bf16x8 pb = as_bf16x8(pw);
	v_add_f32_e32 v62, v109, v62
	v_sub_f32_e32 v111, v111, v63
	v_mul_f32_e32 v111, 0x3fb8aa3b, v111
	v_exp_f32_e32 v111, v111
	v_add_f32_e32 v62, v110, v62
	v_sub_f32_e32 v112, v112, v63
	v_mul_f32_e32 v112, 0x3fb8aa3b, v112
	v_exp_f32_e32 v112, v112
	v_add_f32_e32 v62, v111, v62
	v_sub_f32_e32 v113, v113, v63
	v_mul_f32_e32 v113, 0x3fb8aa3b, v113
	v_exp_f32_e32 v113, v113
	v_add_f32_e32 v62, v112, v62
	v_sub_f32_e32 v114, v114, v63
	v_mul_f32_e32 v114, 0x3fb8aa3b, v114
	v_exp_f32_e32 v114, v114
	v_add_f32_e32 v62, v113, v62
	v_sub_f32_e32 v115, v115, v63
	v_mul_f32_e32 v115, 0x3fb8aa3b, v115
	v_exp_f32_e32 v115, v115
	v_add_f32_e32 v62, v114, v62
	v_sub_f32_e32 v116, v116, v63
	v_mul_f32_e32 v116, 0x3fb8aa3b, v116
	v_exp_f32_e32 v116, v116
	v_add_f32_e32 v62, v115, v62
	v_sub_f32_e32 v117, v117, v63
	v_mul_f32_e32 v117, 0x3fb8aa3b, v117
	v_exp_f32_e32 v117, v117
	v_add_f32_e32 v62, v116, v62
	v_sub_f32_e32 v118, v118, v63
	v_mul_f32_e32 v118, 0x3fb8aa3b, v118
	v_exp_f32_e32 v118, v118
	v_add_f32_e32 v62, v117, v62
	v_sub_f32_e32 v119, v119, v63
	v_mul_f32_e32 v119, 0x3fb8aa3b, v119
	v_exp_f32_e32 v119, v119
	v_add_f32_e32 v62, v118, v62
	v_sub_f32_e32 v120, v120, v63
	v_mul_f32_e32 v120, 0x3fb8aa3b, v120
	v_exp_f32_e32 v120, v120
	v_add_f32_e32 v62, v119, v62
	v_sub_f32_e32 v121, v121, v63
	v_mul_f32_e32 v121, 0x3fb8aa3b, v121
	v_exp_f32_e32 v121, v121
	v_add_f32_e32 v62, v120, v62
	v_sub_f32_e32 v122, v122, v63
	v_mul_f32_e32 v122, 0x3fb8aa3b, v122
	v_exp_f32_e32 v122, v122
	v_add_f32_e32 v62, v121, v62
	v_sub_f32_e32 v123, v123, v63
	v_mul_f32_e32 v123, 0x3fb8aa3b, v123
	v_exp_f32_e32 v123, v123
	v_add_f32_e32 v62, v122, v62
	v_sub_f32_e32 v124, v124, v63
	v_mul_f32_e32 v124, 0x3fb8aa3b, v124
	v_exp_f32_e32 v124, v124
	v_add_f32_e32 v62, v123, v62
	v_sub_f32_e32 v125, v125, v63
	v_mul_f32_e32 v125, 0x3fb8aa3b, v125
	v_exp_f32_e32 v125, v125
	v_add_f32_e32 v62, v124, v62
	v_sub_f32_e32 v126, v126, v63
	v_mul_f32_e32 v126, 0x3fb8aa3b, v126
	v_exp_f32_e32 v126, v126
	v_add_f32_e32 v62, v125, v62
	v_sub_f32_e32 v127, v127, v63
	v_mul_f32_e32 v127, 0x3fb8aa3b, v127
	v_exp_f32_e32 v127, v127
	v_add_f32_e32 v62, v126, v62
	s_nop 0
	v_add_f32_e32 v62, v127, v62
	ds_bpermute_b32 v8, v6, v62
	s_waitcnt lgkmcnt(0)
	v_add_f32_e32 v62, v62, v8
	ds_bpermute_b32 v8, v7, v62
	s_waitcnt lgkmcnt(0)
	v_add_f32_e32 v0, v62, v8
	v_div_scale_f32 v8, s[18:19], v0, v0, 1.0
	v_rcp_f32_e32 v9, v8
	s_nop 0
	v_fma_f32 v136, -v8, v9, 1.0
	v_fmac_f32_e32 v9, v136, v9
	v_div_scale_f32 v136, vcc, 1.0, v0, 1.0
	v_mul_f32_e32 v137, v136, v9
	v_fma_f32 v62, -v8, v137, v136
	v_fmac_f32_e32 v137, v62, v9
	v_fma_f32 v8, -v8, v137, v136
	v_div_fmas_f32 v8, v8, v9, v137
	v_div_fixup_f32 v62, v8, v0, 1.0
	v_pk_mul_f32 v[8:9], v[64:65], v[62:63] op_sel_hi:[1,0]
	v_cvt_pk_bf16_f32 v64, v8, v9
	v_pk_mul_f32 v[8:9], v[66:67], v[62:63] op_sel_hi:[1,0]
	v_cvt_pk_bf16_f32 v65, v8, v9
	v_pk_mul_f32 v[8:9], v[68:69], v[62:63] op_sel_hi:[1,0]
	v_cvt_pk_bf16_f32 v66, v8, v9
	v_pk_mul_f32 v[8:9], v[70:71], v[62:63] op_sel_hi:[1,0]
	v_cvt_pk_bf16_f32 v67, v8, v9
	v_pk_mul_f32 v[8:9], v[72:73], v[62:63] op_sel_hi:[1,0]
	v_cvt_pk_bf16_f32 v68, v8, v9
	v_pk_mul_f32 v[8:9], v[74:75], v[62:63] op_sel_hi:[1,0]
	v_cvt_pk_bf16_f32 v69, v8, v9
	v_pk_mul_f32 v[8:9], v[76:77], v[62:63] op_sel_hi:[1,0]
	v_cvt_pk_bf16_f32 v70, v8, v9
	v_pk_mul_f32 v[8:9], v[78:79], v[62:63] op_sel_hi:[1,0]
	v_cvt_pk_bf16_f32 v71, v8, v9
	v_pk_mul_f32 v[8:9], v[80:81], v[62:63] op_sel_hi:[1,0]
	v_cvt_pk_bf16_f32 v72, v8, v9
	v_pk_mul_f32 v[8:9], v[82:83], v[62:63] op_sel_hi:[1,0]
	v_cvt_pk_bf16_f32 v73, v8, v9
	v_pk_mul_f32 v[8:9], v[84:85], v[62:63] op_sel_hi:[1,0]
	v_cvt_pk_bf16_f32 v74, v8, v9
	v_pk_mul_f32 v[8:9], v[86:87], v[62:63] op_sel_hi:[1,0]
	v_cvt_pk_bf16_f32 v75, v8, v9
	v_pk_mul_f32 v[8:9], v[88:89], v[62:63] op_sel_hi:[1,0]
	v_cvt_pk_bf16_f32 v76, v8, v9
	v_pk_mul_f32 v[8:9], v[90:91], v[62:63] op_sel_hi:[1,0]
	v_cvt_pk_bf16_f32 v77, v8, v9
	v_pk_mul_f32 v[8:9], v[92:93], v[62:63] op_sel_hi:[1,0]
	v_cvt_pk_bf16_f32 v78, v8, v9
	v_pk_mul_f32 v[8:9], v[94:95], v[62:63] op_sel_hi:[1,0]
	v_cvt_pk_bf16_f32 v79, v8, v9
	v_pk_mul_f32 v[8:9], v[96:97], v[62:63] op_sel_hi:[1,0]
	v_cvt_pk_bf16_f32 v80, v8, v9
	v_pk_mul_f32 v[8:9], v[98:99], v[62:63] op_sel_hi:[1,0]
	v_cvt_pk_bf16_f32 v81, v8, v9
	v_pk_mul_f32 v[8:9], v[100:101], v[62:63] op_sel_hi:[1,0]
	v_cvt_pk_bf16_f32 v82, v8, v9
	v_pk_mul_f32 v[8:9], v[102:103], v[62:63] op_sel_hi:[1,0]
	v_cvt_pk_bf16_f32 v83, v8, v9
	v_pk_mul_f32 v[8:9], v[104:105], v[62:63] op_sel_hi:[1,0]
	v_cvt_pk_bf16_f32 v84, v8, v9
	v_pk_mul_f32 v[8:9], v[106:107], v[62:63] op_sel_hi:[1,0]
	v_cvt_pk_bf16_f32 v85, v8, v9
	v_pk_mul_f32 v[8:9], v[108:109], v[62:63] op_sel_hi:[1,0]
	v_cvt_pk_bf16_f32 v86, v8, v9
	v_pk_mul_f32 v[8:9], v[110:111], v[62:63] op_sel_hi:[1,0]
	v_cvt_pk_bf16_f32 v87, v8, v9
	v_pk_mul_f32 v[8:9], v[112:113], v[62:63] op_sel_hi:[1,0]
	v_cvt_pk_bf16_f32 v88, v8, v9
	v_pk_mul_f32 v[8:9], v[114:115], v[62:63] op_sel_hi:[1,0]
	v_cvt_pk_bf16_f32 v89, v8, v9
	v_pk_mul_f32 v[8:9], v[116:117], v[62:63] op_sel_hi:[1,0]
	v_cvt_pk_bf16_f32 v90, v8, v9
	v_pk_mul_f32 v[8:9], v[118:119], v[62:63] op_sel_hi:[1,0]
	v_cvt_pk_bf16_f32 v91, v8, v9
	v_pk_mul_f32 v[8:9], v[120:121], v[62:63] op_sel_hi:[1,0]
	v_cvt_pk_bf16_f32 v92, v8, v9
	v_pk_mul_f32 v[8:9], v[122:123], v[62:63] op_sel_hi:[1,0]
	v_cvt_pk_bf16_f32 v93, v8, v9
	v_pk_mul_f32 v[8:9], v[124:125], v[62:63] op_sel_hi:[1,0]
	v_cvt_pk_bf16_f32 v94, v8, v9
	v_pk_mul_f32 v[8:9], v[126:127], v[62:63] op_sel_hi:[1,0]
	v_cvt_pk_bf16_f32 v95, v8, v9
	s_cmp_lg_u32 s28, 0
	s_cbranch_scc1 .Lxp_nopf
	s_cmpk_lg_i32 s88, 0x100
	s_cbranch_scc1 .Lxp_nopf
	s_add_u32 s22, s22, 0x20000
	s_addc_u32 s23, s23, 0
	s_add_u32 s24, s24, 0x20000
	s_addc_u32 s25, s25, 0
	global_load_dwordx4 v[96:99], v2, s[22:23] offset:0
	global_load_dwordx4 v[100:103], v2, s[22:23] offset:64
	global_load_dwordx4 v[104:107], v2, s[22:23] offset:128
	global_load_dwordx4 v[108:111], v2, s[22:23] offset:192
	global_load_dwordx4 v[112:115], v2, s[24:25] offset:0
	global_load_dwordx4 v[116:119], v2, s[24:25] offset:64
	global_load_dwordx4 v[120:123], v2, s[24:25] offset:128
	global_load_dwordx4 v[124:127], v2, s[24:25] offset:192
; #define MFMA16(a, b, c) __builtin_amdgcn_mfma_f32_16x16x32_bf16((a), (b), (c), 0, 0, 0)
; __device__ __forceinline__ unsigned pk2(float lo, float hi) { return pg8::cvt_pk_bf16(lo, hi); }
; __device__ __forceinline__ void xattn_prompt_item(const bf16_t* xq, const bf16_t* xq1, const bf16_t* memkv, const bf16_t* memvt, bf16_t* xo, int l, int it, int lane) {
;     ...
; #pragma unroll
;     for (int u = 0; u < 8; ++u) {
;         u32x4 pw; pw.x = pk2(sc[2 * u][0] * inv, sc[2 * u][1] * inv); pw.y = pk2(sc[2 * u][2] * inv, sc[2 * u][3] * inv);
;         pw.z = pk2(sc[2 * u + 1][0] * inv, sc[2 * u + 1][1] * inv); pw.w = pk2(sc[2 * u + 1][2] * inv, sc[2 * u + 1][3] * inv);
;         const bf16x8 pb = as_bf16x8(pw);
;         const int pos0 = 32 * u + 4 * g;
; #pragma unroll
;         for (int mi = 0; mi < 8; ++mi) {
;             const bf16_t* vp = memvt + ((size_t)((l * 2 + b) * 512 + h * 128 + 16 * mi + l15)) * 256 + pos0;
;             const s16x4 v0 = *(const s16x4*)vp, v1 = *(const s16x4*)(vp + 16);
;             const bf16x8 va = (bf16x8){v0[0], v0[1], v0[2], v0[3], v1[0], v1[1], v1[2], v1[3]};
;             o[mi] = MFMA16(va, pb, o[mi]);
;         }
;     }
.Lxp_nopf:
	s_nop 1
	ds_read_b128 v[178:181], v4 offset:64
	ds_read_b128 v[182:185], v4 offset:8512
	ds_read_b128 v[186:189], v4 offset:16960
	ds_read_b128 v[190:193], v4 offset:25408
	s_waitcnt lgkmcnt(4)
	v_mfma_f32_16x16x32_bf16 v[26:29], v[146:149], v[64:67], 0
	v_mfma_f32_16x16x32_bf16 v[30:33], v[150:153], v[64:67], 0
	ds_read_b128 v[194:197], v4 offset:33856
	v_mfma_f32_16x16x32_bf16 v[34:37], v[154:157], v[64:67], 0
	v_mfma_f32_16x16x32_bf16 v[38:41], v[158:161], v[64:67], 0
	ds_read_b128 v[198:201], v4 offset:42304
	v_mfma_f32_16x16x32_bf16 v[42:45], v[162:165], v[64:67], 0
	v_mfma_f32_16x16x32_bf16 v[46:49], v[166:169], v[64:67], 0
	ds_read_b128 v[202:205], v4 offset:50752
	v_mfma_f32_16x16x32_bf16 v[50:53], v[170:173], v[64:67], 0
	v_mfma_f32_16x16x32_bf16 v[54:57], v[174:177], v[64:67], 0
	ds_read_b128 v[206:209], v4 offset:59200
	ds_read_b128 v[146:149], v4 offset:128
	ds_read_b128 v[150:153], v4 offset:8576
	ds_read_b128 v[154:157], v4 offset:17024
	ds_read_b128 v[158:161], v4 offset:25472
	s_waitcnt lgkmcnt(4)
	v_mfma_f32_16x16x32_bf16 v[26:29], v[178:181], v[68:71], v[26:29]
	v_mfma_f32_16x16x32_bf16 v[30:33], v[182:185], v[68:71], v[30:33]
	ds_read_b128 v[162:165], v4 offset:33920
	v_mfma_f32_16x16x32_bf16 v[34:37], v[186:189], v[68:71], v[34:37]
	v_mfma_f32_16x16x32_bf16 v[38:41], v[190:193], v[68:71], v[38:41]
	ds_read_b128 v[166:169], v4 offset:42368
	v_mfma_f32_16x16x32_bf16 v[42:45], v[194:197], v[68:71], v[42:45]
	v_mfma_f32_16x16x32_bf16 v[46:49], v[198:201], v[68:71], v[46:49]
	ds_read_b128 v[170:173], v4 offset:50816
	v_mfma_f32_16x16x32_bf16 v[50:53], v[202:205], v[68:71], v[50:53]
	v_mfma_f32_16x16x32_bf16 v[54:57], v[206:209], v[68:71], v[54:57]
	ds_read_b128 v[174:177], v4 offset:59264
	ds_read_b128 v[178:181], v4 offset:192
	ds_read_b128 v[182:185], v4 offset:8640
	ds_read_b128 v[186:189], v4 offset:17088
	ds_read_b128 v[190:193], v4 offset:25536
	s_waitcnt lgkmcnt(4)
	v_mfma_f32_16x16x32_bf16 v[26:29], v[146:149], v[72:75], v[26:29]
	v_mfma_f32_16x16x32_bf16 v[30:33], v[150:153], v[72:75], v[30:33]
	ds_read_b128 v[194:197], v4 offset:33984
	v_mfma_f32_16x16x32_bf16 v[34:37], v[154:157], v[72:75], v[34:37]
	v_mfma_f32_16x16x32_bf16 v[38:41], v[158:161], v[72:75], v[38:41]
	ds_read_b128 v[198:201], v4 offset:42432
	v_mfma_f32_16x16x32_bf16 v[42:45], v[162:165], v[72:75], v[42:45]
	v_mfma_f32_16x16x32_bf16 v[46:49], v[166:169], v[72:75], v[46:49]
	ds_read_b128 v[202:205], v4 offset:50880
	v_mfma_f32_16x16x32_bf16 v[50:53], v[170:173], v[72:75], v[50:53]
	v_mfma_f32_16x16x32_bf16 v[54:57], v[174:177], v[72:75], v[54:57]
	ds_read_b128 v[206:209], v4 offset:59328
	ds_read_b128 v[146:149], v4 offset:256
	ds_read_b128 v[150:153], v4 offset:8704
	ds_read_b128 v[154:157], v4 offset:17152
	ds_read_b128 v[158:161], v4 offset:25600
	s_waitcnt lgkmcnt(4)
	v_mfma_f32_16x16x32_bf16 v[26:29], v[178:181], v[76:79], v[26:29]
	v_mfma_f32_16x16x32_bf16 v[30:33], v[182:185], v[76:79], v[30:33]
	ds_read_b128 v[162:165], v4 offset:34048
	v_mfma_f32_16x16x32_bf16 v[34:37], v[186:189], v[76:79], v[34:37]
	v_mfma_f32_16x16x32_bf16 v[38:41], v[190:193], v[76:79], v[38:41]
	ds_read_b128 v[166:169], v4 offset:42496
	v_mfma_f32_16x16x32_bf16 v[42:45], v[194:197], v[76:79], v[42:45]
	v_mfma_f32_16x16x32_bf16 v[46:49], v[198:201], v[76:79], v[46:49]
	ds_read_b128 v[170:173], v4 offset:50944
	v_mfma_f32_16x16x32_bf16 v[50:53], v[202:205], v[76:79], v[50:53]
	v_mfma_f32_16x16x32_bf16 v[54:57], v[206:209], v[76:79], v[54:57]
	ds_read_b128 v[174:177], v4 offset:59392
	ds_read_b128 v[178:181], v4 offset:320
	ds_read_b128 v[182:185], v4 offset:8768
	ds_read_b128 v[186:189], v4 offset:17216
	ds_read_b128 v[190:193], v4 offset:25664
	s_waitcnt lgkmcnt(4)
; #define MFMA16(a, b, c) __builtin_amdgcn_mfma_f32_16x16x32_bf16((a), (b), (c), 0, 0, 0)
; __device__ __forceinline__ unsigned pk2(float lo, float hi) { return pg8::cvt_pk_bf16(lo, hi); }
; __device__ __forceinline__ void xattn_prompt_item(const bf16_t* xq, const bf16_t* xq1, const bf16_t* memkv, const bf16_t* memvt, bf16_t* xo, int l, int it, int lane) {
;     ...
; #pragma unroll
;     for (int u = 0; u < 8; ++u) {
;         u32x4 pw; pw.x = pk2(sc[2 * u][0] * inv, sc[2 * u][1] * inv); pw.y = pk2(sc[2 * u][2] * inv, sc[2 * u][3] * inv);
;         pw.z = pk2(sc[2 * u + 1][0] * inv, sc[2 * u + 1][1] * inv); pw.w = pk2(sc[2 * u + 1][2] * inv, sc[2 * u + 1][3] * inv);
;         const bf16x8 pb = as_bf16x8(pw);
;         const int pos0 = 32 * u + 4 * g;
; #pragma unroll
;         for (int mi = 0; mi < 8; ++mi) {
;             const bf16_t* vp = memvt + ((size_t)((l * 2 + b) * 512 + h * 128 + 16 * mi + l15)) * 256 + pos0;
;             const s16x4 v0 = *(const s16x4*)vp, v1 = *(const s16x4*)(vp + 16);
;             const bf16x8 va = (bf16x8){v0[0], v0[1], v0[2], v0[3], v1[0], v1[1], v1[2], v1[3]};
;             o[mi] = MFMA16(va, pb, o[mi]);
;         }
;     }
; #pragma unroll
;     for (int mi = 0; mi < 8; ++mi) {
;         u32x2 w; w.x = pk2(o[mi][0], o[mi][1]); w.y = pk2(o[mi][2], o[mi][3]);
;         *(u32x2*)(xo + tok * 512 + h * 128 + 16 * mi + 4 * g) = w;
	v_mfma_f32_16x16x32_bf16 v[26:29], v[146:149], v[80:83], v[26:29]
	v_mfma_f32_16x16x32_bf16 v[30:33], v[150:153], v[80:83], v[30:33]
	ds_read_b128 v[194:197], v4 offset:34112
	v_mfma_f32_16x16x32_bf16 v[34:37], v[154:157], v[80:83], v[34:37]
	v_mfma_f32_16x16x32_bf16 v[38:41], v[158:161], v[80:83], v[38:41]
	ds_read_b128 v[198:201], v4 offset:42560
	v_mfma_f32_16x16x32_bf16 v[42:45], v[162:165], v[80:83], v[42:45]
	v_mfma_f32_16x16x32_bf16 v[46:49], v[166:169], v[80:83], v[46:49]
	ds_read_b128 v[202:205], v4 offset:51008
	v_mfma_f32_16x16x32_bf16 v[50:53], v[170:173], v[80:83], v[50:53]
	v_mfma_f32_16x16x32_bf16 v[54:57], v[174:177], v[80:83], v[54:57]
	ds_read_b128 v[206:209], v4 offset:59456
	ds_read_b128 v[146:149], v4 offset:384
	ds_read_b128 v[150:153], v4 offset:8832
	ds_read_b128 v[154:157], v4 offset:17280
	ds_read_b128 v[158:161], v4 offset:25728
	s_waitcnt lgkmcnt(4)
	v_mfma_f32_16x16x32_bf16 v[26:29], v[178:181], v[84:87], v[26:29]
	v_mfma_f32_16x16x32_bf16 v[30:33], v[182:185], v[84:87], v[30:33]
	ds_read_b128 v[162:165], v4 offset:34176
	v_mfma_f32_16x16x32_bf16 v[34:37], v[186:189], v[84:87], v[34:37]
	v_mfma_f32_16x16x32_bf16 v[38:41], v[190:193], v[84:87], v[38:41]
	ds_read_b128 v[166:169], v4 offset:42624
	v_mfma_f32_16x16x32_bf16 v[42:45], v[194:197], v[84:87], v[42:45]
	v_mfma_f32_16x16x32_bf16 v[46:49], v[198:201], v[84:87], v[46:49]
	ds_read_b128 v[170:173], v4 offset:51072
	v_mfma_f32_16x16x32_bf16 v[50:53], v[202:205], v[84:87], v[50:53]
	v_mfma_f32_16x16x32_bf16 v[54:57], v[206:209], v[84:87], v[54:57]
	ds_read_b128 v[174:177], v4 offset:59520
	ds_read_b128 v[178:181], v4 offset:448
	ds_read_b128 v[182:185], v4 offset:8896
	ds_read_b128 v[186:189], v4 offset:17344
	ds_read_b128 v[190:193], v4 offset:25792
	s_waitcnt lgkmcnt(4)
	v_mfma_f32_16x16x32_bf16 v[26:29], v[146:149], v[88:91], v[26:29]
	v_mfma_f32_16x16x32_bf16 v[30:33], v[150:153], v[88:91], v[30:33]
	ds_read_b128 v[194:197], v4 offset:34240
	v_mfma_f32_16x16x32_bf16 v[34:37], v[154:157], v[88:91], v[34:37]
	v_mfma_f32_16x16x32_bf16 v[38:41], v[158:161], v[88:91], v[38:41]
	ds_read_b128 v[198:201], v4 offset:42688
	v_mfma_f32_16x16x32_bf16 v[42:45], v[162:165], v[88:91], v[42:45]
	v_mfma_f32_16x16x32_bf16 v[46:49], v[166:169], v[88:91], v[46:49]
	ds_read_b128 v[202:205], v4 offset:51136
	v_mfma_f32_16x16x32_bf16 v[50:53], v[170:173], v[88:91], v[50:53]
	v_mfma_f32_16x16x32_bf16 v[54:57], v[174:177], v[88:91], v[54:57]
	ds_read_b128 v[206:209], v4 offset:59584
	s_waitcnt lgkmcnt(0)
	v_mfma_f32_16x16x32_bf16 v[26:29], v[178:181], v[92:95], v[26:29]
	v_mfma_f32_16x16x32_bf16 v[30:33], v[182:185], v[92:95], v[30:33]
	v_mfma_f32_16x16x32_bf16 v[34:37], v[186:189], v[92:95], v[34:37]
	v_mfma_f32_16x16x32_bf16 v[38:41], v[190:193], v[92:95], v[38:41]
	v_mfma_f32_16x16x32_bf16 v[42:45], v[194:197], v[92:95], v[42:45]
	v_mfma_f32_16x16x32_bf16 v[46:49], v[198:201], v[92:95], v[46:49]
	v_mfma_f32_16x16x32_bf16 v[50:53], v[202:205], v[92:95], v[50:53]
	v_mfma_f32_16x16x32_bf16 v[54:57], v[206:209], v[92:95], v[54:57]
	s_nop 7
	v_cvt_pk_bf16_f32 v8, v26, v27
	v_cvt_pk_bf16_f32 v9, v28, v29
	global_store_dwordx2 v5, v[8:9], s[4:5] offset:0
	s_nop 0
	v_cvt_pk_bf16_f32 v8, v30, v31
	v_cvt_pk_bf16_f32 v9, v32, v33
	global_store_dwordx2 v5, v[8:9], s[4:5] offset:32
	s_nop 0
	v_cvt_pk_bf16_f32 v8, v34, v35
	v_cvt_pk_bf16_f32 v9, v36, v37
	global_store_dwordx2 v5, v[8:9], s[4:5] offset:64
	s_nop 0
	v_cvt_pk_bf16_f32 v8, v38, v39
	v_cvt_pk_bf16_f32 v9, v40, v41
	global_store_dwordx2 v5, v[8:9], s[4:5] offset:96
	s_nop 0
	v_cvt_pk_bf16_f32 v8, v42, v43
	v_cvt_pk_bf16_f32 v9, v44, v45
	global_store_dwordx2 v5, v[8:9], s[4:5] offset:128
	s_nop 0
	v_cvt_pk_bf16_f32 v8, v46, v47
	v_cvt_pk_bf16_f32 v9, v48, v49
	global_store_dwordx2 v5, v[8:9], s[4:5] offset:160
	s_nop 0
	v_cvt_pk_bf16_f32 v8, v50, v51
	v_cvt_pk_bf16_f32 v9, v52, v53
	global_store_dwordx2 v5, v[8:9], s[4:5] offset:192
	s_nop 0
	v_cvt_pk_bf16_f32 v8, v54, v55
	v_cvt_pk_bf16_f32 v9, v56, v57
	global_store_dwordx2 v5, v[8:9], s[4:5] offset:224
	s_nop 0
	s_cmpk_eq_i32 s88, 0x100
	s_cbranch_scc0 .Lxp_next
	s_cmp_lg_u32 s28, 0
	s_cbranch_scc1 .LBB0_1405
	s_mov_b32 s28, 1
	s_add_i32 s6, s6, 4
	s_branch .Lxp_pair
